# v35: v34 + non-temporal hint on the RWKV scan's chunk staging loads (each element read once)
# speedup vs baseline: 1.0147x; 1.0002x over previous
.LBB0_1176:
	s_or_b64 exec, exec, s[4:5]
	s_lshl_b32 s3, s2, 3
	s_and_b32 s3, s3, 56
	s_ashr_i32 s6, s2, 5
	s_add_i32 s3, s3, s6
	s_ashr_i32 s4, s3, 3
	v_ashrrev_i32_e32 v70, 4, v39
	s_ashr_i32 s5, s4, 31
	v_bfe_u32 v75, v39, 3, 4
	s_lshl_b64 s[8:9], s[4:5], 11
	v_ashrrev_i32_e32 v71, 31, v70
	v_or_b32_e32 v0, s8, v75
	v_mov_b32_e32 v1, s9
	s_lshl_b32 s3, s6, 6
	v_lshl_add_u64 v[72:73], s[8:9], 0, v[70:71]
	v_lshlrev_b64 v[4:5], 10, v[0:1]
	s_and_b32 s3, s3, 0x1c0
	v_lshlrev_b32_e32 v2, 3, v39
	v_lshlrev_b64 v[8:9], 11, v[72:73]
	v_and_b32_e32 v89, 15, v39
	v_lshl_add_u64 v[0:1], v[32:33], 0, v[4:5]
	s_lshl_b32 s6, s3, 1
	v_and_b32_e32 v42, 56, v2
	v_lshl_add_u64 v[4:5], v[34:35], 0, v[4:5]
	v_lshl_add_u64 v[8:9], s[84:85], 0, v[8:9]
	s_lshl_b32 s10, s3, 2
	s_mov_b32 s11, s7
	v_lshl_add_u64 v[0:1], v[0:1], 0, s[6:7]
	v_lshlrev_b32_e32 v68, 1, v42
	v_lshl_add_u64 v[4:5], v[4:5], 0, s[6:7]
	v_lshl_add_u64 v[8:9], v[8:9], 0, s[10:11]
	v_lshlrev_b32_e32 v36, 4, v89
	v_mov_b32_e32 v37, v69
	v_lshl_add_u64 v[0:1], v[0:1], 0, v[68:69]
	v_lshl_add_u64 v[4:5], v[4:5], 0, v[68:69]
	v_lshl_add_u64 v[8:9], v[8:9], 0, v[36:37]
	global_load_dwordx4 v[0:3], v[0:1], off nt
	s_lshl_b32 s3, s2, 1
	global_load_dwordx4 v[4:7], v[4:5], off nt
	v_and_b32_e32 v37, 1, v39
	global_load_dwordx4 v[8:11], v[8:9], off nt
	s_and_b32 s3, s3, 48
	v_bfe_u32 v74, v39, 1, 4
	v_cmp_lt_i32_e32 vcc, 31, v39
	v_cmp_gt_i32_e64 s[4:5], 32, v39
	s_waitcnt vmcnt(4)
	v_lshlrev_b32_e32 v28, 4, v37
	s_and_saveexec_b64 s[14:15], s[4:5]
	s_xor_b64 s[14:15], exec, s[14:15]
	s_cbranch_execz .LBB0_1178
	v_or_b32_e32 v12, s8, v74
	v_mov_b32_e32 v13, s9
	v_lshlrev_b64 v[12:13], 10, v[12:13]
	v_lshl_add_u64 v[12:13], s[62:63], 0, v[12:13]
	v_lshl_add_u64 v[12:13], v[12:13], 0, s[6:7]
	s_lshl_b32 s16, s3, 1
	s_mov_b32 s17, s7
	v_lshl_add_u64 v[12:13], v[12:13], 0, s[16:17]
	v_mov_b32_e32 v29, v69
	v_lshl_add_u64 v[12:13], v[12:13], 0, v[28:29]
	global_load_dwordx4 v[12:15], v[12:13], off nt
.LBB0_1178:
	s_or_b64 exec, exec, s[14:15]
	s_or_b32 s14, s8, 16
	s_mov_b32 s15, s9
	v_mov_b32_e32 v17, s9
	v_or_b32_e32 v16, s14, v75
	v_lshl_add_u64 v[24:25], s[14:15], 0, v[70:71]
	v_lshlrev_b64 v[20:21], 10, v[16:17]
	v_lshlrev_b64 v[24:25], 11, v[24:25]
	v_lshlrev_b32_e32 v38, 2, v89
	v_lshl_add_u64 v[16:17], v[32:33], 0, v[20:21]
	v_lshl_add_u64 v[20:21], v[34:35], 0, v[20:21]
	v_lshl_add_u64 v[24:25], s[84:85], 0, v[24:25]
	v_lshl_add_u64 v[16:17], v[16:17], 0, s[6:7]
	v_lshl_add_u64 v[20:21], v[20:21], 0, s[6:7]
	v_lshl_add_u64 v[24:25], v[24:25], 0, s[10:11]
	v_lshlrev_b32_e32 v76, 2, v38
	v_mov_b32_e32 v77, v69
	v_lshl_add_u64 v[16:17], v[16:17], 0, v[68:69]
	v_lshl_add_u64 v[20:21], v[20:21], 0, v[68:69]
	v_lshl_add_u64 v[24:25], v[24:25], 0, v[76:77]
	global_load_dwordx4 v[16:19], v[16:17], off nt
	s_nop 0
	global_load_dwordx4 v[20:23], v[20:21], off nt
	s_nop 0
	global_load_dwordx4 v[24:27], v[24:25], off nt
	s_and_saveexec_b64 s[16:17], s[4:5]
	s_cbranch_execz .LBB0_1180
	v_or_b32_e32 v30, s14, v74
	v_mov_b32_e32 v31, s15
	v_lshlrev_b64 v[30:31], 10, v[30:31]
	v_lshl_add_u64 v[30:31], s[62:63], 0, v[30:31]
	v_lshl_add_u64 v[30:31], v[30:31], 0, s[6:7]
	s_lshl_b32 s14, s3, 1
	s_mov_b32 s15, s7
	v_lshl_add_u64 v[30:31], v[30:31], 0, s[14:15]
	v_mov_b32_e32 v29, v69
	v_lshl_add_u64 v[28:29], v[30:31], 0, v[28:29]
	global_load_dwordx4 v[28:31], v[28:29], off nt

.LBB0_1187:
	s_add_i32 s3, s20, 2
	s_cmpk_lt_u32 s20, 0x7e
	s_cselect_b64 s[14:15], -1, 0
	s_cmpk_gt_u32 s20, 0x7d
	s_cselect_b64 s[10:11], -1, 0
	s_and_b64 vcc, exec, s[10:11]
	s_cbranch_vccnz .LBB0_1191
	s_lshl_b32 s6, s3, 4
	s_add_u32 s16, s8, s6
	s_addc_u32 s17, s9, 0
	v_mov_b32_e32 v1, s17
	v_or_b32_e32 v0, s16, v75
	v_lshl_add_u64 v[8:9], s[16:17], 0, v[70:71]
	v_lshlrev_b64 v[4:5], 10, v[0:1]
	v_lshlrev_b64 v[8:9], 11, v[8:9]
	v_lshl_add_u64 v[0:1], v[78:79], 0, v[4:5]
	v_lshl_add_u64 v[4:5], v[80:81], 0, v[4:5]
	v_lshl_add_u64 v[8:9], v[82:83], 0, v[8:9]
	global_load_dwordx4 v[0:3], v[0:1], off nt
	s_nop 0
	global_load_dwordx4 v[4:7], v[4:5], off nt
	s_nop 0
	global_load_dwordx4 v[8:11], v[8:9], off nt
	s_and_saveexec_b64 s[18:19], s[4:5]
	s_cbranch_execz .LBB0_1190
	v_mov_b32_e32 v13, s17
	v_or_b32_e32 v12, s16, v74
	v_lshlrev_b64 v[12:13], 10, v[12:13]
	v_lshl_add_u64 v[12:13], v[84:85], 0, v[12:13]
	global_load_dwordx4 v[12:15], v[12:13], off nt

.LBB0_1197:
	s_or_b64 exec, exec, s[16:17]
	s_waitcnt lgkmcnt(0)
	s_barrier
	ds_read_b32 v34, v99 offset:43008
	s_lshl_b32 s6, s20, 4
	v_lshl_add_u64 v[32:33], v[72:73], 0, s[6:7]
	v_lshlrev_b64 v[32:33], 11, v[32:33]
	v_lshl_add_u64 v[32:33], v[86:87], 0, v[32:33]
	s_cmpk_gt_u32 s20, 0x7c
	s_waitcnt lgkmcnt(0)
	global_store_dword v[32:33], v34, off nt
	s_cbranch_scc1 .LBB0_1201
	s_add_i32 s16, s6, 48
	s_add_u32 s16, s8, s16
	s_addc_u32 s17, s9, 0
	v_mov_b32_e32 v17, s17
	v_or_b32_e32 v16, s16, v75
	v_lshl_add_u64 v[24:25], s[16:17], 0, v[70:71]
	v_lshlrev_b64 v[20:21], 10, v[16:17]
	v_lshlrev_b64 v[24:25], 11, v[24:25]
	v_lshl_add_u64 v[16:17], v[78:79], 0, v[20:21]
	v_lshl_add_u64 v[20:21], v[80:81], 0, v[20:21]
	v_lshl_add_u64 v[24:25], v[82:83], 0, v[24:25]
	global_load_dwordx4 v[16:19], v[16:17], off nt
	s_nop 0
	global_load_dwordx4 v[20:23], v[20:21], off nt
	s_nop 0
	global_load_dwordx4 v[24:27], v[24:25], off nt
	s_and_saveexec_b64 s[18:19], s[4:5]
	s_cbranch_execz .LBB0_1200
	v_mov_b32_e32 v29, s17
	v_or_b32_e32 v28, s16, v74
	v_lshlrev_b64 v[28:29], 10, v[28:29]
	v_lshl_add_u64 v[28:29], v[84:85], 0, v[28:29]
	global_load_dwordx4 v[28:31], v[28:29], off nt
